# input-projection GEMM: first K-iteration peeled with srcC=0 on first-touch MFMAs, 128-mov accumulator zero-init removed
# baseline (speedup 1.0000x reference)
.Lsw_done:
	s_ashr_i32 s21, s20, 31
	s_lshl_b64 s[14:15], s[20:21], 19
	s_add_u32 s14, s90, s14
	s_addc_u32 s15, s91, s15
	s_and_b64 s[16:17], s[44:45], exec
	s_cselect_b32 s21, s15, s23
	s_cselect_b32 s28, s14, s22
	s_ashr_i32 s19, s18, 31
	s_lshl_b64 s[16:17], s[18:19], 19
	s_add_u32 s16, s5, s16
	s_addc_u32 s17, s89, s17
	s_and_b64 s[26:27], s[44:45], exec
	s_cselect_b32 s19, s17, s25
	s_cselect_b32 s29, s16, s24
	s_add_u32 s22, s22, 0x40080
	s_addc_u32 s23, s23, 0
	s_add_u32 s30, s24, 0x100
	s_addc_u32 s31, s25, 0
	s_mov_b32 s34, -2
	s_add_u32 s24, s22, 0xfffc0080
	s_addc_u32 s25, s23, -1
	s_add_i32 s35, 0, 0x10000
	s_cmp_eq_u32 s34, 12
	s_cselect_b32 s27, s21, s25
	s_cselect_b32 s26, s28, s24
	v_add_u32_e32 v128, s35, v184
	s_cselect_b32 s25, s19, s31
	s_cselect_b32 s24, s29, s30
	s_add_i32 s38, 0, 0x14000
	ds_read_b128 v[130:133], v128
	ds_read_b128 v[134:137], v128 offset:1024
	ds_read_b128 v[138:141], v128 offset:2048
	ds_read_b128 v[142:145], v128 offset:3072
	v_add_u32_e32 v128, s38, v184
	ds_read_b128 v[154:157], v128
	ds_read_b128 v[158:161], v128 offset:1024
	ds_read_b128 v[162:165], v128 offset:2048
	ds_read_b128 v[166:169], v128 offset:3072
	v_lshl_add_u64 v[206:207], s[22:23], 0, v[150:151]
	s_add_i32 m0, s73, 0xc000
	ds_read_b128 v[170:173], v185
	ds_read_b128 v[174:177], v185 offset:1024
	ds_read_b128 v[178:181], v185 offset:2048
	ds_read_b128 v[186:189], v185 offset:3072
	ds_read_b128 v[190:193], v185 offset:4096
	ds_read_b128 v[194:197], v185 offset:5120
	ds_read_b128 v[198:201], v185 offset:6144
	ds_read_b128 v[202:205], v185 offset:7168
	global_load_lds_dwordx4 v[206:207], off
	v_lshl_add_u64 v[206:207], s[22:23], 0, v[152:153]
	s_add_i32 m0, s73, 0xe000
	s_nop 0
	global_load_lds_dwordx4 v[206:207], off
	s_waitcnt vmcnt(8)
	s_waitcnt lgkmcnt(0)
	s_barrier
	s_setprio 1
	s_waitcnt lgkmcnt(0)
	v_mfma_f32_16x16x32_bf16 v[124:127], v[130:133], v[170:173], 0
	v_mfma_f32_16x16x32_bf16 v[120:123], v[138:141], v[170:173], 0
	v_mfma_f32_16x16x32_bf16 v[108:111], v[130:133], v[178:181], 0
	v_mfma_f32_16x16x32_bf16 v[104:107], v[138:141], v[178:181], 0
	v_mfma_f32_16x16x32_bf16 v[92:95], v[130:133], v[190:193], 0
	v_mfma_f32_16x16x32_bf16 v[88:91], v[138:141], v[190:193], 0
	v_mfma_f32_16x16x32_bf16 v[76:79], v[130:133], v[198:201], 0
	v_mfma_f32_16x16x32_bf16 v[72:75], v[138:141], v[198:201], 0
	v_mfma_f32_16x16x32_bf16 v[124:127], v[134:137], v[174:177], v[124:127]
	v_mfma_f32_16x16x32_bf16 v[120:123], v[142:145], v[174:177], v[120:123]
	v_mfma_f32_16x16x32_bf16 v[108:111], v[134:137], v[186:189], v[108:111]
	v_mfma_f32_16x16x32_bf16 v[104:107], v[142:145], v[186:189], v[104:107]
	v_mfma_f32_16x16x32_bf16 v[92:95], v[134:137], v[194:197], v[92:95]
	v_mfma_f32_16x16x32_bf16 v[88:91], v[142:145], v[194:197], v[88:91]
	v_mfma_f32_16x16x32_bf16 v[76:79], v[134:137], v[202:205], v[76:79]
	v_mfma_f32_16x16x32_bf16 v[72:75], v[142:145], v[202:205], v[72:75]
	s_setprio 0
	s_setprio 1
	v_mfma_f32_16x16x32_bf16 v[116:119], v[154:157], v[170:173], 0
	v_mfma_f32_16x16x32_bf16 v[112:115], v[162:165], v[170:173], 0
	v_mfma_f32_16x16x32_bf16 v[100:103], v[154:157], v[178:181], 0
	v_mfma_f32_16x16x32_bf16 v[96:99], v[162:165], v[178:181], 0
	v_mfma_f32_16x16x32_bf16 v[84:87], v[154:157], v[190:193], 0
	v_mfma_f32_16x16x32_bf16 v[80:83], v[162:165], v[190:193], 0
	v_mfma_f32_16x16x32_bf16 v[68:71], v[154:157], v[198:201], 0
	v_mfma_f32_16x16x32_bf16 v[64:67], v[162:165], v[198:201], 0
	v_mfma_f32_16x16x32_bf16 v[116:119], v[158:161], v[174:177], v[116:119]
	v_mfma_f32_16x16x32_bf16 v[112:115], v[166:169], v[174:177], v[112:115]
	v_mfma_f32_16x16x32_bf16 v[100:103], v[158:161], v[186:189], v[100:103]
	v_mfma_f32_16x16x32_bf16 v[96:99], v[166:169], v[186:189], v[96:99]
	v_mfma_f32_16x16x32_bf16 v[84:87], v[158:161], v[194:197], v[84:87]
	v_mfma_f32_16x16x32_bf16 v[80:83], v[166:169], v[194:197], v[80:83]
	v_mfma_f32_16x16x32_bf16 v[68:71], v[158:161], v[202:205], v[68:71]
	v_mfma_f32_16x16x32_bf16 v[64:67], v[166:169], v[202:205], v[64:67]
	s_setprio 0
	s_barrier
	s_add_i32 s35, s35, s4
	v_lshl_add_u64 v[206:207], s[24:25], 0, v[146:147]
	s_mov_b32 m0, s35
	ds_read_b128 v[170:173], v185 offset:16384
	ds_read_b128 v[174:177], v185 offset:17408
	ds_read_b128 v[178:181], v185 offset:18432
	ds_read_b128 v[186:189], v185 offset:19456
	ds_read_b128 v[190:193], v185 offset:20480
	ds_read_b128 v[194:197], v185 offset:21504
	ds_read_b128 v[198:201], v185 offset:22528
	ds_read_b128 v[202:205], v185 offset:23552
	global_load_lds_dwordx4 v[206:207], off
	s_add_i32 m0, s35, 0x2000
	s_add_u32 s36, s24, 0x40000
	v_lshl_add_u64 v[208:209], s[24:25], 0, v[148:149]
	s_addc_u32 s37, s25, 0
	s_add_i32 s35, s38, s4
	global_load_lds_dwordx4 v[208:209], off
	v_lshl_add_u64 v[210:211], s[36:37], 0, v[146:147]
	s_mov_b32 m0, s35
	v_lshl_add_u64 v[212:213], s[26:27], 0, v[148:149]
	global_load_lds_dwordx4 v[210:211], off
	v_lshl_add_u64 v[210:211], s[36:37], 0, v[148:149]
	s_add_i32 m0, s35, 0x2000
	s_nop 0
	global_load_lds_dwordx4 v[210:211], off
	v_lshl_add_u64 v[210:211], s[26:27], 0, v[146:147]
	s_mov_b32 m0, s73
	s_nop 0
	global_load_lds_dwordx4 v[210:211], off
	s_mov_b32 m0, s93
	s_nop 0
	global_load_lds_dwordx4 v[212:213], off
	s_waitcnt vmcnt(8)
	s_waitcnt lgkmcnt(0)
	s_barrier
	s_setprio 1
	s_waitcnt lgkmcnt(0)
	v_mfma_f32_16x16x32_bf16 v[60:63], v[130:133], v[170:173], 0
	v_mfma_f32_16x16x32_bf16 v[56:59], v[138:141], v[170:173], 0
	v_mfma_f32_16x16x32_bf16 v[44:47], v[130:133], v[178:181], 0
	v_mfma_f32_16x16x32_bf16 v[40:43], v[138:141], v[178:181], 0
	v_mfma_f32_16x16x32_bf16 v[28:31], v[130:133], v[190:193], 0
	v_mfma_f32_16x16x32_bf16 v[24:27], v[138:141], v[190:193], 0
	v_mfma_f32_16x16x32_bf16 v[12:15], v[130:133], v[198:201], 0
	v_mfma_f32_16x16x32_bf16 v[8:11], v[138:141], v[198:201], 0
	v_mfma_f32_16x16x32_bf16 v[60:63], v[134:137], v[174:177], v[60:63]
	v_mfma_f32_16x16x32_bf16 v[56:59], v[142:145], v[174:177], v[56:59]
	v_mfma_f32_16x16x32_bf16 v[44:47], v[134:137], v[186:189], v[44:47]
	v_mfma_f32_16x16x32_bf16 v[40:43], v[142:145], v[186:189], v[40:43]
	v_mfma_f32_16x16x32_bf16 v[28:31], v[134:137], v[194:197], v[28:31]
	v_mfma_f32_16x16x32_bf16 v[24:27], v[142:145], v[194:197], v[24:27]
	v_mfma_f32_16x16x32_bf16 v[12:15], v[134:137], v[202:205], v[12:15]
	v_mfma_f32_16x16x32_bf16 v[8:11], v[142:145], v[202:205], v[8:11]
	s_setprio 0
	s_setprio 1
	v_mfma_f32_16x16x32_bf16 v[52:55], v[154:157], v[170:173], 0
	v_mfma_f32_16x16x32_bf16 v[48:51], v[162:165], v[170:173], 0
	v_mfma_f32_16x16x32_bf16 v[36:39], v[154:157], v[178:181], 0
	v_mfma_f32_16x16x32_bf16 v[32:35], v[162:165], v[178:181], 0
	v_mfma_f32_16x16x32_bf16 v[20:23], v[154:157], v[190:193], 0
	v_mfma_f32_16x16x32_bf16 v[16:19], v[162:165], v[190:193], 0
	v_mfma_f32_16x16x32_bf16 v[4:7], v[154:157], v[198:201], 0
	v_mfma_f32_16x16x32_bf16 v[0:3], v[162:165], v[198:201], 0
	v_mfma_f32_16x16x32_bf16 v[52:55], v[158:161], v[174:177], v[52:55]
	v_mfma_f32_16x16x32_bf16 v[48:51], v[166:169], v[174:177], v[48:51]
	v_mfma_f32_16x16x32_bf16 v[36:39], v[158:161], v[186:189], v[36:39]
	v_mfma_f32_16x16x32_bf16 v[32:35], v[166:169], v[186:189], v[32:35]
	v_mfma_f32_16x16x32_bf16 v[20:23], v[158:161], v[194:197], v[20:23]
	v_mfma_f32_16x16x32_bf16 v[16:19], v[166:169], v[194:197], v[16:19]
	v_mfma_f32_16x16x32_bf16 v[4:7], v[158:161], v[202:205], v[4:7]
	v_mfma_f32_16x16x32_bf16 v[0:3], v[166:169], v[202:205], v[0:3]
	s_setprio 0
	s_barrier
	s_add_i32 s35, 0, 0x18000
	v_add_u32_e32 v128, s35, v184
	s_add_i32 s36, 0, 0x1c000
	ds_read_b128 v[130:133], v128
	ds_read_b128 v[134:137], v128 offset:1024
	ds_read_b128 v[138:141], v128 offset:2048
	ds_read_b128 v[142:145], v128 offset:3072
	v_add_u32_e32 v128, s36, v184
	ds_read_b128 v[154:157], v128
	ds_read_b128 v[158:161], v128 offset:1024
	ds_read_b128 v[162:165], v128 offset:2048
	ds_read_b128 v[166:169], v128 offset:3072
	s_add_u32 s26, s26, 0x40000
	s_addc_u32 s27, s27, 0
	s_mov_b32 m0, s96
	v_lshl_add_u64 v[214:215], s[26:27], 0, v[146:147]
	ds_read_b128 v[170:173], v185 offset:32768
	ds_read_b128 v[174:177], v185 offset:33792
	ds_read_b128 v[178:181], v185 offset:34816
	ds_read_b128 v[186:189], v185 offset:35840
	ds_read_b128 v[190:193], v185 offset:36864
	ds_read_b128 v[194:197], v185 offset:37888
	ds_read_b128 v[198:201], v185 offset:38912
	ds_read_b128 v[202:205], v185 offset:39936
	global_load_lds_dwordx4 v[214:215], off
	v_lshl_add_u64 v[214:215], s[26:27], 0, v[148:149]
	s_mov_b32 m0, s97
	s_nop 0
	global_load_lds_dwordx4 v[214:215], off
	s_waitcnt vmcnt(8)
	s_waitcnt lgkmcnt(0)
	s_barrier
	s_setprio 1
	s_waitcnt lgkmcnt(0)
	v_mfma_f32_16x16x32_bf16 v[124:127], v[130:133], v[170:173], v[124:127]
	v_mfma_f32_16x16x32_bf16 v[120:123], v[138:141], v[170:173], v[120:123]
	v_mfma_f32_16x16x32_bf16 v[108:111], v[130:133], v[178:181], v[108:111]
	v_mfma_f32_16x16x32_bf16 v[104:107], v[138:141], v[178:181], v[104:107]
	v_mfma_f32_16x16x32_bf16 v[92:95], v[130:133], v[190:193], v[92:95]
	v_mfma_f32_16x16x32_bf16 v[88:91], v[138:141], v[190:193], v[88:91]
	v_mfma_f32_16x16x32_bf16 v[76:79], v[130:133], v[198:201], v[76:79]
	v_mfma_f32_16x16x32_bf16 v[72:75], v[138:141], v[198:201], v[72:75]
	v_mfma_f32_16x16x32_bf16 v[124:127], v[134:137], v[174:177], v[124:127]
	v_mfma_f32_16x16x32_bf16 v[120:123], v[142:145], v[174:177], v[120:123]
	v_mfma_f32_16x16x32_bf16 v[108:111], v[134:137], v[186:189], v[108:111]
	v_mfma_f32_16x16x32_bf16 v[104:107], v[142:145], v[186:189], v[104:107]
	v_mfma_f32_16x16x32_bf16 v[92:95], v[134:137], v[194:197], v[92:95]
	v_mfma_f32_16x16x32_bf16 v[88:91], v[142:145], v[194:197], v[88:91]
	v_mfma_f32_16x16x32_bf16 v[76:79], v[134:137], v[202:205], v[76:79]
	v_mfma_f32_16x16x32_bf16 v[72:75], v[142:145], v[202:205], v[72:75]
	s_setprio 0
	s_setprio 1
	v_mfma_f32_16x16x32_bf16 v[116:119], v[154:157], v[170:173], v[116:119]
	v_mfma_f32_16x16x32_bf16 v[112:115], v[162:165], v[170:173], v[112:115]
	v_mfma_f32_16x16x32_bf16 v[100:103], v[154:157], v[178:181], v[100:103]
	v_mfma_f32_16x16x32_bf16 v[96:99], v[162:165], v[178:181], v[96:99]
	v_mfma_f32_16x16x32_bf16 v[84:87], v[154:157], v[190:193], v[84:87]
	v_mfma_f32_16x16x32_bf16 v[80:83], v[162:165], v[190:193], v[80:83]
	v_mfma_f32_16x16x32_bf16 v[68:71], v[154:157], v[198:201], v[68:71]
	v_mfma_f32_16x16x32_bf16 v[64:67], v[162:165], v[198:201], v[64:67]
	v_mfma_f32_16x16x32_bf16 v[116:119], v[158:161], v[174:177], v[116:119]
	v_mfma_f32_16x16x32_bf16 v[112:115], v[166:169], v[174:177], v[112:115]
	v_mfma_f32_16x16x32_bf16 v[100:103], v[158:161], v[186:189], v[100:103]
	v_mfma_f32_16x16x32_bf16 v[96:99], v[166:169], v[186:189], v[96:99]
	v_mfma_f32_16x16x32_bf16 v[84:87], v[158:161], v[194:197], v[84:87]
	v_mfma_f32_16x16x32_bf16 v[80:83], v[166:169], v[194:197], v[80:83]
	v_mfma_f32_16x16x32_bf16 v[68:71], v[158:161], v[202:205], v[68:71]
	v_mfma_f32_16x16x32_bf16 v[64:67], v[166:169], v[202:205], v[64:67]
	s_setprio 0
	s_barrier
	s_add_i32 s26, s35, s4
	v_lshl_add_u64 v[206:207], v[206:207], 0, s[6:7]
	s_mov_b32 m0, s26
	ds_read_b128 v[170:173], v185 offset:49152
	ds_read_b128 v[174:177], v185 offset:50176
	ds_read_b128 v[178:181], v185 offset:51200
	ds_read_b128 v[186:189], v185 offset:52224
	ds_read_b128 v[190:193], v185 offset:53248
	ds_read_b128 v[194:197], v185 offset:54272
	ds_read_b128 v[198:201], v185 offset:55296
	ds_read_b128 v[202:205], v185 offset:56320
	global_load_lds_dwordx4 v[206:207], off
	s_add_i32 m0, s26, 0x2000
	s_add_u32 s24, s24, 0x40080
	v_lshl_add_u64 v[206:207], v[208:209], 0, s[6:7]
	s_addc_u32 s25, s25, 0
	s_add_i32 s26, s36, s4
	global_load_lds_dwordx4 v[206:207], off
	v_lshl_add_u64 v[206:207], s[24:25], 0, v[146:147]
	s_mov_b32 m0, s26
	s_nop 0
	global_load_lds_dwordx4 v[206:207], off
	v_lshl_add_u64 v[206:207], s[24:25], 0, v[148:149]
	s_add_i32 m0, s26, 0x2000
	s_nop 0
	global_load_lds_dwordx4 v[206:207], off
	v_lshl_add_u64 v[206:207], v[210:211], 0, s[6:7]
	s_mov_b32 m0, s85
	s_nop 0
	global_load_lds_dwordx4 v[206:207], off
	v_lshl_add_u64 v[206:207], v[212:213], 0, s[6:7]
	s_mov_b32 m0, s62
	s_nop 0
	global_load_lds_dwordx4 v[206:207], off
	s_waitcnt vmcnt(8)
	s_waitcnt lgkmcnt(0)
	s_barrier
	s_setprio 1
	s_waitcnt lgkmcnt(0)
	v_mfma_f32_16x16x32_bf16 v[60:63], v[130:133], v[170:173], v[60:63]
	v_mfma_f32_16x16x32_bf16 v[56:59], v[138:141], v[170:173], v[56:59]
	v_mfma_f32_16x16x32_bf16 v[44:47], v[130:133], v[178:181], v[44:47]
	v_mfma_f32_16x16x32_bf16 v[40:43], v[138:141], v[178:181], v[40:43]
	v_mfma_f32_16x16x32_bf16 v[28:31], v[130:133], v[190:193], v[28:31]
	v_mfma_f32_16x16x32_bf16 v[24:27], v[138:141], v[190:193], v[24:27]
	v_mfma_f32_16x16x32_bf16 v[12:15], v[130:133], v[198:201], v[12:15]
	v_mfma_f32_16x16x32_bf16 v[8:11], v[138:141], v[198:201], v[8:11]
	v_mfma_f32_16x16x32_bf16 v[60:63], v[134:137], v[174:177], v[60:63]
	v_mfma_f32_16x16x32_bf16 v[56:59], v[142:145], v[174:177], v[56:59]
	v_mfma_f32_16x16x32_bf16 v[44:47], v[134:137], v[186:189], v[44:47]
	v_mfma_f32_16x16x32_bf16 v[40:43], v[142:145], v[186:189], v[40:43]
	v_mfma_f32_16x16x32_bf16 v[28:31], v[134:137], v[194:197], v[28:31]
	v_mfma_f32_16x16x32_bf16 v[24:27], v[142:145], v[194:197], v[24:27]
	v_mfma_f32_16x16x32_bf16 v[12:15], v[134:137], v[202:205], v[12:15]
	v_mfma_f32_16x16x32_bf16 v[8:11], v[142:145], v[202:205], v[8:11]
	s_setprio 0
	s_setprio 1
	v_mfma_f32_16x16x32_bf16 v[52:55], v[154:157], v[170:173], v[52:55]
	v_mfma_f32_16x16x32_bf16 v[48:51], v[162:165], v[170:173], v[48:51]
	v_mfma_f32_16x16x32_bf16 v[36:39], v[154:157], v[178:181], v[36:39]
	v_mfma_f32_16x16x32_bf16 v[32:35], v[162:165], v[178:181], v[32:35]
	v_mfma_f32_16x16x32_bf16 v[20:23], v[154:157], v[190:193], v[20:23]
	v_mfma_f32_16x16x32_bf16 v[16:19], v[162:165], v[190:193], v[16:19]
	v_mfma_f32_16x16x32_bf16 v[4:7], v[154:157], v[198:201], v[4:7]
	v_mfma_f32_16x16x32_bf16 v[0:3], v[162:165], v[198:201], v[0:3]
	v_mfma_f32_16x16x32_bf16 v[52:55], v[158:161], v[174:177], v[52:55]
	v_mfma_f32_16x16x32_bf16 v[48:51], v[166:169], v[174:177], v[48:51]
	v_mfma_f32_16x16x32_bf16 v[36:39], v[158:161], v[186:189], v[36:39]
	v_mfma_f32_16x16x32_bf16 v[32:35], v[166:169], v[186:189], v[32:35]
	v_mfma_f32_16x16x32_bf16 v[20:23], v[158:161], v[194:197], v[20:23]
	v_mfma_f32_16x16x32_bf16 v[16:19], v[166:169], v[194:197], v[16:19]
	v_mfma_f32_16x16x32_bf16 v[4:7], v[158:161], v[202:205], v[4:7]
	v_mfma_f32_16x16x32_bf16 v[0:3], v[166:169], v[202:205], v[0:3]
	s_setprio 0
	s_barrier
	s_add_i32 s34, s34, 2
	s_add_u32 s22, s22, 0x100
	s_addc_u32 s23, s23, 0
	s_add_u32 s30, s30, 0x100
	s_addc_u32 s31, s31, 0
	s_cmp_gt_u32 s34, 13
	s_cbranch_scc1 .Lpa_peel_exit

.Lpa_peel_exit:
	s_and_b64 vcc, exec, s[58:59]
	s_cbranch_vccz .LBB0_392
	s_barrier
